# no grid barrier after the context LayerNorm phases: rows on workgroups 192-255, counter release; one wave per workgroup acquires before the next GEMM's first epilogue, then a workgroup barrier
# speedup vs baseline: 1.1550x; 1.0108x over previous
.LBB0_923:
	v_writelane_b32 v255, s0, 40
	v_writelane_b32 v255, s1, 41
	v_writelane_b32 v255, s2, 42
	v_writelane_b32 v255, s3, 43
	v_writelane_b32 v255, s4, 44
	v_readlane_b32 s2, v254, 44
	v_readlane_b32 s3, v255, 62
	s_nop 3
	s_cmp_eq_u32 s2, s3
	s_cbranch_scc1 .Lacq_done_f
	s_cmp_eq_u32 s2, 6
	s_cbranch_scc0 .Lacq_done_f
	v_readfirstlane_b32 s4, v191
	s_nop 3
	s_cmp_lt_u32 s4, 64
	s_cbranch_scc0 .Lacq_bar_f
	v_readlane_b32 s0, v254, 10
	v_readlane_b32 s1, v254, 11
	s_nop 3
	s_add_u32 s0, s0, 0x16800
	s_addc_u32 s1, s1, 0
	s_mov_b32 s3, 0

.Lacq_bar_f:
	s_barrier
	v_writelane_b32 v255, s2, 62

.LBB0_943:
	v_writelane_b32 v255, s0, 40
	v_writelane_b32 v255, s1, 41
	v_writelane_b32 v255, s2, 42
	v_writelane_b32 v255, s3, 43
	v_writelane_b32 v255, s4, 44
	v_readlane_b32 s2, v254, 44
	v_readlane_b32 s3, v255, 62
	s_nop 3
	s_cmp_eq_u32 s2, s3
	s_cbranch_scc1 .Lacq_done_b
	s_cmp_eq_u32 s2, 9
	s_cbranch_scc0 .Lacq_done_b
	v_readfirstlane_b32 s4, v191
	s_nop 3
	s_cmp_lt_u32 s4, 64
	s_cbranch_scc0 .Lacq_bar_b
	v_readlane_b32 s0, v254, 10
	v_readlane_b32 s1, v254, 11
	s_nop 3
	s_add_u32 s0, s0, 0x16900
	s_addc_u32 s1, s1, 0
	s_mov_b32 s3, 0
